# v040 + in-proj epilogue: all 8 per-row sum-of-squares loads issued up front instead of one per 32-row group
# speedup vs baseline: 1.0315x; 1.0082x over previous
; template <int EPI>
; DI void gemm_tile(const Params& p, int layer, int mt, int nt, u16* sm, int wv) {
;     ...
;   if (EPI == 0) {
;     const float* ssl = p.ss + (size_t)layer * MTOK;
;     __syncthreads();
;     u16* stg = sm + (wm * 2 + wn) * (128 * LSTR);
;     if (!vtile) {
;       const float qsc = (nt < 2) ? 0.17677669529663687f * LOG2E
;                         : ((nt >= 8 && nt < 12) || nt == 18 || nt == 19) ? 0.125f * LOG2E : 1.f;
; #pragma unroll
;       for (int i = 0; i < 8; ++i) {
;         const int m = m0 + wm * 128 + 16 * i + fr;
;         const float rs = __builtin_amdgcn_rsqf(ssl[m] * (1.f / DM) + EPS) * qsc;
;         u16* d = stg + (16 * i + fr) * LSTR + 4 * fq;
; #pragma unroll
;         for (int j = 0; j < 4; ++j) {
;           u32x2 v = {pk2(acc[i][j][0] * rs, acc[i][j][1] * rs), pk2(acc[i][j][2] * rs, acc[i][j][3] * rs)};
;           *(u32x2*)(d + 16 * j) = v;
;         }
;       }
.LBB0_124:
	s_waitcnt vmcnt(8)
	v_mbcnt_lo_u32_b32 v138, -1, 0
	v_mbcnt_hi_u32_b32 v138, -1, v138
	s_lshl_b32 s21, s21, 8
	v_add_u32_e32 v0, s33, v138
	v_bfe_u32 v130, v0, 6, 21
	s_waitcnt vmcnt(7)
	v_mul_u32_u24_e32 v135, 0x4800, v130
	v_and_b32_e32 v130, 0xffffff80, v0
	v_and_b32_e32 v137, 15, v138
	v_bfe_u32 v134, v138, 4, 2
	v_bfe_u32 v131, v0, 6, 1
	s_mov_b64 s[6:7], -1
	s_andn2_b64 vcc, exec, s[4:5]
	v_add_u32_e32 v139, s21, v130
	v_lshlrev_b32_e32 v136, 4, v138
	s_barrier
	s_cbranch_vccnz .LBB0_126
	v_or_b32_e32 v132, v139, v137
	v_ashrrev_i32_e32 v133, 31, v132
	v_lshl_add_u64 v[132:133], v[132:133], 2, s[0:1]
	global_load_dword v142, v[132:133], off
	global_load_dword v150, v[132:133], off offset:64
	global_load_dword v151, v[132:133], off offset:128
	global_load_dword v152, v[132:133], off offset:192
	global_load_dword v153, v[132:133], off offset:256
	global_load_dword v154, v[132:133], off offset:320
	global_load_dword v155, v[132:133], off offset:384
	global_load_dword v156, v[132:133], off offset:448
	s_and_b32 s4, s20, 0x7ffffffc
	s_cmp_eq_u32 s4, 8
	s_cselect_b64 s[4:5], -1, 0
	s_and_b32 s6, s18, -16
	s_cmpk_eq_i32 s6, 0x90
	s_cselect_b64 s[6:7], -1, 0
	s_or_b64 vcc, s[6:7], s[4:5]
	s_cmp_gt_i32 s20, 1
	v_cndmask_b32_e32 v0, 1.0, v191, vcc
	s_cselect_b64 vcc, -1, 0
	v_cndmask_b32_e32 v0, v192, v0, vcc
	s_waitcnt vmcnt(7)
	v_mul_u32_u24_e32 v143, 0x90, v137
	v_lshlrev_b32_e32 v141, 3, v134
	v_add3_u32 v141, v135, v141, v143
	v_and_b32_e32 v140, 63, v138
	s_mov_b64 s[6:7], 0
	s_waitcnt vmcnt(0)
	v_fmamk_f32 v142, v142, 0x3a800000, v188
	v_rsq_f32_e32 v142, v142
	s_nop 0
	v_mul_f32_e32 v142, v0, v142
	v_pk_mul_f32 v[144:145], v[126:127], v[142:143] op_sel_hi:[1,0]
	v_pk_mul_f32 v[146:147], v[128:129], v[142:143] op_sel_hi:[1,0]
	v_cvt_pk_bf16_f32 v144, v144, v145
	v_cvt_pk_bf16_f32 v145, v146, v147
	v_pk_mul_f32 v[146:147], v[122:123], v[142:143] op_sel_hi:[1,0]
	v_pk_mul_f32 v[148:149], v[124:125], v[142:143] op_sel_hi:[1,0]
	v_cvt_pk_bf16_f32 v146, v146, v147
	v_cvt_pk_bf16_f32 v147, v148, v149
	ds_write2_b64 v141, v[144:145], v[146:147] offset1:4
	v_pk_mul_f32 v[144:145], v[118:119], v[142:143] op_sel_hi:[1,0]
	v_pk_mul_f32 v[146:147], v[120:121], v[142:143] op_sel_hi:[1,0]
	v_cvt_pk_bf16_f32 v144, v144, v145
	v_cvt_pk_bf16_f32 v145, v146, v147
	v_pk_mul_f32 v[146:147], v[114:115], v[142:143] op_sel_hi:[1,0]
	v_pk_mul_f32 v[142:143], v[116:117], v[142:143] op_sel_hi:[1,0]
	v_cvt_pk_bf16_f32 v146, v146, v147
	v_cvt_pk_bf16_f32 v147, v142, v143
	v_mov_b32_e32 v142, v150
	ds_write2_b64 v141, v[144:145], v[146:147] offset0:8 offset1:12
	s_waitcnt vmcnt(0)
	v_fmamk_f32 v142, v142, 0x3a800000, v188
	v_rsq_f32_e32 v142, v142
	s_nop 0
	v_mul_f32_e32 v142, v0, v142
	v_pk_mul_f32 v[144:145], v[110:111], v[142:143] op_sel_hi:[1,0]
	v_pk_mul_f32 v[146:147], v[112:113], v[142:143] op_sel_hi:[1,0]
	v_cvt_pk_bf16_f32 v144, v144, v145
	v_cvt_pk_bf16_f32 v145, v146, v147
	v_pk_mul_f32 v[146:147], v[106:107], v[142:143] op_sel_hi:[1,0]
	v_pk_mul_f32 v[148:149], v[108:109], v[142:143] op_sel_hi:[1,0]
	v_cvt_pk_bf16_f32 v146, v146, v147
	v_cvt_pk_bf16_f32 v147, v148, v149
	v_add_u32_e32 v148, 0x800, v141
	ds_write2_b64 v148, v[144:145], v[146:147] offset0:32 offset1:36
	v_pk_mul_f32 v[144:145], v[102:103], v[142:143] op_sel_hi:[1,0]
	v_pk_mul_f32 v[146:147], v[104:105], v[142:143] op_sel_hi:[1,0]
	v_cvt_pk_bf16_f32 v144, v144, v145
	v_cvt_pk_bf16_f32 v145, v146, v147
	v_pk_mul_f32 v[146:147], v[98:99], v[142:143] op_sel_hi:[1,0]
	v_pk_mul_f32 v[142:143], v[100:101], v[142:143] op_sel_hi:[1,0]
	v_cvt_pk_bf16_f32 v146, v146, v147
	v_cvt_pk_bf16_f32 v147, v142, v143
	v_mov_b32_e32 v142, v151
	ds_write2_b64 v148, v[144:145], v[146:147] offset0:40 offset1:44
	s_waitcnt vmcnt(0)
	v_fmamk_f32 v142, v142, 0x3a800000, v188
	v_rsq_f32_e32 v142, v142
	s_nop 0
	v_mul_f32_e32 v142, v0, v142
	v_pk_mul_f32 v[144:145], v[94:95], v[142:143] op_sel_hi:[1,0]
	v_pk_mul_f32 v[146:147], v[96:97], v[142:143] op_sel_hi:[1,0]
	v_cvt_pk_bf16_f32 v144, v144, v145
	v_cvt_pk_bf16_f32 v145, v146, v147
	v_pk_mul_f32 v[146:147], v[90:91], v[142:143] op_sel_hi:[1,0]
	v_pk_mul_f32 v[148:149], v[92:93], v[142:143] op_sel_hi:[1,0]
	v_cvt_pk_bf16_f32 v146, v146, v147
	v_cvt_pk_bf16_f32 v147, v148, v149
	v_add_u32_e32 v148, 0x1000, v141
	ds_write2_b64 v148, v[144:145], v[146:147] offset0:64 offset1:68
	v_pk_mul_f32 v[144:145], v[86:87], v[142:143] op_sel_hi:[1,0]
	v_pk_mul_f32 v[146:147], v[88:89], v[142:143] op_sel_hi:[1,0]
	v_cvt_pk_bf16_f32 v144, v144, v145
	v_cvt_pk_bf16_f32 v145, v146, v147
	v_pk_mul_f32 v[146:147], v[82:83], v[142:143] op_sel_hi:[1,0]
	v_pk_mul_f32 v[142:143], v[84:85], v[142:143] op_sel_hi:[1,0]
	v_cvt_pk_bf16_f32 v146, v146, v147
	v_cvt_pk_bf16_f32 v147, v142, v143
	v_mov_b32_e32 v142, v152
	ds_write2_b64 v148, v[144:145], v[146:147] offset0:72 offset1:76
	s_waitcnt vmcnt(0)
	v_fmamk_f32 v142, v142, 0x3a800000, v188
	v_rsq_f32_e32 v142, v142
	s_nop 0
	v_mul_f32_e32 v142, v0, v142
	v_pk_mul_f32 v[144:145], v[78:79], v[142:143] op_sel_hi:[1,0]
	v_pk_mul_f32 v[146:147], v[80:81], v[142:143] op_sel_hi:[1,0]
	v_cvt_pk_bf16_f32 v144, v144, v145
	v_cvt_pk_bf16_f32 v145, v146, v147
	v_pk_mul_f32 v[146:147], v[74:75], v[142:143] op_sel_hi:[1,0]
	v_pk_mul_f32 v[148:149], v[76:77], v[142:143] op_sel_hi:[1,0]
	v_cvt_pk_bf16_f32 v146, v146, v147
	v_cvt_pk_bf16_f32 v147, v148, v149
	v_add_u32_e32 v148, 0x1800, v141
	ds_write2_b64 v148, v[144:145], v[146:147] offset0:96 offset1:100
	v_pk_mul_f32 v[144:145], v[70:71], v[142:143] op_sel_hi:[1,0]
	v_pk_mul_f32 v[146:147], v[72:73], v[142:143] op_sel_hi:[1,0]
	v_cvt_pk_bf16_f32 v144, v144, v145
	v_cvt_pk_bf16_f32 v145, v146, v147
	v_pk_mul_f32 v[146:147], v[66:67], v[142:143] op_sel_hi:[1,0]
	v_pk_mul_f32 v[142:143], v[68:69], v[142:143] op_sel_hi:[1,0]
	v_cvt_pk_bf16_f32 v146, v146, v147
	v_cvt_pk_bf16_f32 v147, v142, v143
	v_mov_b32_e32 v142, v153
	ds_write2_b64 v148, v[144:145], v[146:147] offset0:104 offset1:108
	s_waitcnt vmcnt(0)
; template <int EPI>
; DI void gemm_tile(const Params& p, int layer, int mt, int nt, u16* sm, int wv) {
;     ...
;       for (int i = 0; i < 8; ++i) {
;         const int m = m0 + wm * 128 + 16 * i + fr;
;         const float rs = __builtin_amdgcn_rsqf(ssl[m] * (1.f / DM) + EPS) * qsc;
;         u16* d = stg + (16 * i + fr) * LSTR + 4 * fq;
; #pragma unroll
;         for (int j = 0; j < 4; ++j) {
;           u32x2 v = {pk2(acc[i][j][0] * rs, acc[i][j][1] * rs), pk2(acc[i][j][2] * rs, acc[i][j][3] * rs)};
;           *(u32x2*)(d + 16 * j) = v;
;         }
;       }
;       u16* gdst = p.proj + (size_t)(m0 + wm * 128) * DIN + n0 + wn * 64;
; #pragma unroll
;       for (int t = 0; t < 16; ++t) {
;         const int c = lane + 64 * t, row = c >> 3, kc = c & 7;
;         const u32x4 v = *(const u32x4*)(stg + row * LSTR + kc * 8);
;         *(u32x4*)(gdst + (size_t)row * DIN + kc * 8) = v;
;       }
	v_fmamk_f32 v142, v142, 0x3a800000, v188
	v_rsq_f32_e32 v142, v142
	s_nop 0
	v_mul_f32_e32 v142, v0, v142
	v_pk_mul_f32 v[144:145], v[62:63], v[142:143] op_sel_hi:[1,0]
	v_pk_mul_f32 v[146:147], v[64:65], v[142:143] op_sel_hi:[1,0]
	v_cvt_pk_bf16_f32 v144, v144, v145
	v_cvt_pk_bf16_f32 v145, v146, v147
	v_pk_mul_f32 v[146:147], v[58:59], v[142:143] op_sel_hi:[1,0]
	v_pk_mul_f32 v[148:149], v[60:61], v[142:143] op_sel_hi:[1,0]
	v_cvt_pk_bf16_f32 v146, v146, v147
	v_cvt_pk_bf16_f32 v147, v148, v149
	v_add_u32_e32 v148, 0x2000, v141
	ds_write2_b64 v148, v[144:145], v[146:147] offset0:128 offset1:132
	v_pk_mul_f32 v[144:145], v[54:55], v[142:143] op_sel_hi:[1,0]
	v_pk_mul_f32 v[146:147], v[56:57], v[142:143] op_sel_hi:[1,0]
	v_cvt_pk_bf16_f32 v144, v144, v145
	v_cvt_pk_bf16_f32 v145, v146, v147
	v_pk_mul_f32 v[146:147], v[50:51], v[142:143] op_sel_hi:[1,0]
	v_pk_mul_f32 v[142:143], v[52:53], v[142:143] op_sel_hi:[1,0]
	v_cvt_pk_bf16_f32 v146, v146, v147
	v_cvt_pk_bf16_f32 v147, v142, v143
	v_mov_b32_e32 v142, v154
	ds_write2_b64 v148, v[144:145], v[146:147] offset0:136 offset1:140
	s_waitcnt vmcnt(0)
	v_fmamk_f32 v142, v142, 0x3a800000, v188
	v_rsq_f32_e32 v142, v142
	s_nop 0
	v_mul_f32_e32 v142, v0, v142
	v_pk_mul_f32 v[144:145], v[46:47], v[142:143] op_sel_hi:[1,0]
	v_pk_mul_f32 v[146:147], v[48:49], v[142:143] op_sel_hi:[1,0]
	v_cvt_pk_bf16_f32 v144, v144, v145
	v_cvt_pk_bf16_f32 v145, v146, v147
	v_pk_mul_f32 v[146:147], v[42:43], v[142:143] op_sel_hi:[1,0]
	v_pk_mul_f32 v[148:149], v[44:45], v[142:143] op_sel_hi:[1,0]
	v_cvt_pk_bf16_f32 v146, v146, v147
	v_cvt_pk_bf16_f32 v147, v148, v149
	v_add_u32_e32 v148, 0x2800, v141
	ds_write2_b64 v148, v[144:145], v[146:147] offset0:160 offset1:164
	v_pk_mul_f32 v[144:145], v[38:39], v[142:143] op_sel_hi:[1,0]
	v_pk_mul_f32 v[146:147], v[40:41], v[142:143] op_sel_hi:[1,0]
	v_cvt_pk_bf16_f32 v144, v144, v145
	v_cvt_pk_bf16_f32 v145, v146, v147
	v_pk_mul_f32 v[146:147], v[34:35], v[142:143] op_sel_hi:[1,0]
	v_pk_mul_f32 v[142:143], v[36:37], v[142:143] op_sel_hi:[1,0]
	v_cvt_pk_bf16_f32 v146, v146, v147
	v_cvt_pk_bf16_f32 v147, v142, v143
	v_mov_b32_e32 v142, v155
	ds_write2_b64 v148, v[144:145], v[146:147] offset0:168 offset1:172
	v_mov_b32_e32 v132, v156
	s_waitcnt vmcnt(1)
	v_fmamk_f32 v142, v142, 0x3a800000, v188
	v_rsq_f32_e32 v142, v142
	s_waitcnt vmcnt(0)
	v_fmamk_f32 v132, v132, 0x3a800000, v188
	v_rsq_f32_e32 v132, v132
	v_mul_f32_e32 v142, v0, v142
	v_pk_mul_f32 v[144:145], v[30:31], v[142:143] op_sel_hi:[1,0]
	v_pk_mul_f32 v[146:147], v[32:33], v[142:143] op_sel_hi:[1,0]
	v_cvt_pk_bf16_f32 v144, v144, v145
	v_cvt_pk_bf16_f32 v145, v146, v147
	v_pk_mul_f32 v[146:147], v[26:27], v[142:143] op_sel_hi:[1,0]
	v_pk_mul_f32 v[148:149], v[28:29], v[142:143] op_sel_hi:[1,0]
	v_cvt_pk_bf16_f32 v146, v146, v147
	v_cvt_pk_bf16_f32 v147, v148, v149
	v_add_u32_e32 v148, 0x3000, v141
	ds_write2_b64 v148, v[144:145], v[146:147] offset0:192 offset1:196
	v_pk_mul_f32 v[144:145], v[22:23], v[142:143] op_sel_hi:[1,0]
	v_pk_mul_f32 v[146:147], v[24:25], v[142:143] op_sel_hi:[1,0]
	v_cvt_pk_bf16_f32 v144, v144, v145
	v_cvt_pk_bf16_f32 v145, v146, v147
	v_pk_mul_f32 v[146:147], v[18:19], v[142:143] op_sel_hi:[1,0]
	v_pk_mul_f32 v[142:143], v[20:21], v[142:143] op_sel_hi:[1,0]
	v_mul_f32_e32 v0, v0, v132
	v_cvt_pk_bf16_f32 v146, v146, v147
	v_cvt_pk_bf16_f32 v147, v142, v143
	v_pk_mul_f32 v[132:133], v[14:15], v[0:1] op_sel_hi:[1,0]
	v_pk_mul_f32 v[142:143], v[16:17], v[0:1] op_sel_hi:[1,0]
	ds_write2_b64 v148, v[144:145], v[146:147] offset0:200 offset1:204
	v_cvt_pk_bf16_f32 v132, v132, v133
	v_cvt_pk_bf16_f32 v133, v142, v143
	v_pk_mul_f32 v[142:143], v[6:7], v[0:1] op_sel_hi:[1,0]
	v_pk_mul_f32 v[144:145], v[8:9], v[0:1] op_sel_hi:[1,0]
	v_cvt_pk_bf16_f32 v142, v142, v143
	v_cvt_pk_bf16_f32 v143, v144, v145
	v_add_u32_e32 v141, 0x3800, v141
	ds_write2_b64 v141, v[132:133], v[142:143] offset0:224 offset1:228
	v_pk_mul_f32 v[132:133], v[2:3], v[0:1] op_sel_hi:[1,0]
	v_pk_mul_f32 v[142:143], v[4:5], v[0:1] op_sel_hi:[1,0]
	v_cvt_pk_bf16_f32 v132, v132, v133
	v_cvt_pk_bf16_f32 v133, v142, v143
	v_pk_mul_f32 v[142:143], v[10:11], v[0:1] op_sel_hi:[1,0]
	v_pk_mul_f32 v[144:145], v[12:13], v[0:1] op_sel_hi:[1,0]
	v_cvt_pk_bf16_f32 v142, v142, v143
	v_cvt_pk_bf16_f32 v143, v144, v145
	ds_write2_b64 v141, v[132:133], v[142:143] offset0:232 offset1:236
	v_mov_b64_e32 v[132:133], s[62:63]
	v_mad_i64_i32 v[132:133], s[4:5], v139, s8, v[132:133]
	v_lshl_add_u64 v[132:133], s[2:3], 1, v[132:133]
	v_lshlrev_b32_e32 v0, 7, v131
	v_lshrrev_b32_e32 v148, 3, v140
	v_lshl_add_u64 v[132:133], v[132:133], 0, v[0:1]
	v_and_b32_e32 v0, 0x70, v136
	v_mul_u32_u24_e32 v140, 0x90, v148
	v_add3_u32 v149, v135, v0, v140
	ds_read_b128 v[140:143], v149
	v_lshl_add_u64 v[132:133], v[132:133], 0, v[0:1]
	v_mul_u32_u24_e32 v0, 0xd00, v148
	v_lshlrev_b32_e32 v0, 1, v0
	v_lshl_add_u64 v[144:145], v[132:133], 0, v[0:1]
	s_cmp_eq_u32 s40, 2
	s_cbranch_scc1 .Lepi_hi_skip
	s_waitcnt lgkmcnt(0)
	global_store_dwordx4 v[144:145], v[140:143], off
	ds_read_b128 v[140:143], v149 offset:1152
	s_mov_b32 s2, 0xd000
	v_add_co_u32_e32 v146, vcc, s2, v144
	s_mov_b32 s2, 0x1a000
	s_nop 0
	v_addc_co_u32_e32 v147, vcc, 0, v145, vcc
	s_waitcnt lgkmcnt(0)
	global_store_dwordx4 v[146:147], v[140:143], off
	ds_read_b128 v[140:143], v149 offset:2304
	v_add_co_u32_e32 v146, vcc, s2, v144
	s_mov_b32 s2, 0x27000
	s_nop 0
	v_addc_co_u32_e32 v147, vcc, 0, v145, vcc
	s_waitcnt lgkmcnt(0)
	global_store_dwordx4 v[146:147], v[140:143], off
	ds_read_b128 v[140:143], v149 offset:3456
	v_add_co_u32_e32 v144, vcc, s2, v144
	s_movk_i32 s2, 0xd00
	s_nop 0
	v_addc_co_u32_e32 v145, vcc, 0, v145, vcc
	s_waitcnt lgkmcnt(0)
	global_store_dwordx4 v[144:145], v[140:143], off
	ds_read_b128 v[140:143], v149 offset:4608
	v_add_u32_e32 v144, 0x34000, v0
	v_mov_b32_e32 v145, v1
	v_lshl_add_u64 v[144:145], v[132:133], 0, v[144:145]
	s_waitcnt lgkmcnt(0)
	global_store_dwordx4 v[144:145], v[140:143], off
	ds_read_b128 v[140:143], v149 offset:5760
	v_add_u32_e32 v144, 0x41000, v0
	v_mov_b32_e32 v145, v1
	v_lshl_add_u64 v[144:145], v[132:133], 0, v[144:145]
	s_waitcnt lgkmcnt(0)
	global_store_dwordx4 v[144:145], v[140:143], off
	ds_read_b128 v[140:143], v149 offset:6912
	v_add_u32_e32 v144, 0x4e000, v0
	v_mov_b32_e32 v145, v1
	v_lshl_add_u64 v[144:145], v[132:133], 0, v[144:145]
	s_waitcnt lgkmcnt(0)
	global_store_dwordx4 v[144:145], v[140:143], off
	ds_read_b128 v[140:143], v149 offset:8064
	v_add_u32_e32 v144, 0x5b000, v0
	v_mov_b32_e32 v145, v1
	v_lshl_add_u64 v[144:145], v[132:133], 0, v[144:145]
	s_waitcnt lgkmcnt(0)
	global_store_dwordx4 v[144:145], v[140:143], off
	s_cmp_eq_u32 s40, 1
	s_cbranch_scc1 .Lgx_halfdone
	s_branch .Lepi_t8

; DI void attn_item_A(const Params& p, int layer, int b, int head, int qb, u16* sm, float lam, float lam_init, int wv) {
;     ...
;   const int t7 = tid & 127, wp = t7 >> 6;
;   const int csrc = (lane & 7) ^ ((4 * wp + (lane >> 4)) & 7);
;   const int row0 = wp * 8 + (lane >> 3);
;   const u16* kg = projb + koff + csrc * 8;
;   const u16* vg = p.vt + ((size_t)(b * NVH + vh) * 64) * SEQ + csrc * 8;
;   float zf = 0.f;
;   asm volatile("" : "+v"(zf));
;   f32x16 o[2][2];
; #pragma unroll
;   for (int a = 0; a < 2; ++a)
; #pragma unroll
;     for (int d = 0; d < 2; ++d)
; #pragma unroll
;       for (int e = 0; e < 16; ++e) o[a][d][e] = zf;
;   float m0 = 0.f, m1 = 0.f;
;   f32x4 ls0 = {zf, zf, zf, zf}, ls1 = {zf, zf, zf, zf};
;   const bf16x8 ones = rowsum_ones(lane);
;   bool started = false;
;   const int npairs = (qb >> 1) + 1;
;   const int T0 = 2 * (npairs - 1) + kh;
;   const bool v0 = (T0 <= qb);
;   auto dma_tile = [&](int T, int c) {
;     const int k0 = 64 * T;
;     u16* Kd = Kb0 + c * (2 * 64 * 64) + wp * (8 * 64);
; #pragma unroll
;     for (int i = 0; i < 4; ++i) {
;       __builtin_amdgcn_global_load_lds((const unsigned*)(kg + (size_t)(k0 + row0 + 16 * i) * DIN), (unsigned*)(Kd + i * 16 * 64), 16, 0, 0);
;       __builtin_amdgcn_global_load_lds((const unsigned*)(vg + (size_t)(row0 + 16 * i) * SEQ + k0), (unsigned*)(Kd + 64 * 64 + i * 16 * 64), 16, 0, 0);
;     }
;   };
.LBB0_276:
	s_or_b64 exec, exec, s[18:19]
	s_waitcnt vmcnt(0)
	v_and_b32_e32 v205, 60, v125
	s_waitcnt vmcnt(0) lgkmcnt(0)
	s_barrier
	s_and_saveexec_b64 s[18:19], vcc
	s_cbranch_execz .LBB0_292
	v_add_u32_e32 v66, v120, v171
	v_sub_u32_e32 v66, v66, v124
	v_lshlrev_b32_e32 v67, 6, v118
	v_sub_u32_e32 v66, v66, v67
	v_lshlrev_b32_e32 v206, 6, v173
	v_lshlrev_b32_e32 v67, 6, v119
	v_sub_u32_e32 v66, v66, v206
	v_and_b32_e32 v67, 0xffffff80, v67
	v_sub_u32_e32 v66, v66, v67
	v_add_u32_e32 v207, 0x2040, v66
	v_add_u32_e32 v66, v118, v173
	s_movk_i32 s2, 0xff7f
	v_add3_u32 v208, v66, v123, s2
	v_or_b32_e32 v66, v121, v67
	v_cmp_gt_u32_e64 s[36:37], 16, v171
	v_add_u32_e32 v209, v66, v122
	v_add_u32_e32 v210, 0xffffff00, v67
	v_add_u32_e32 v72, v206, v209
	v_add_u32_e32 v68, 0xffffff00, v72
	v_mad_i64_i32 v[68:69], s[38:39], v68, s8, v[160:161]
	v_readlane_b32 s22, v250, 19
	v_add_u32_e32 v66, v206, v210
	v_ashrrev_i32_e32 v67, 31, v66
	v_lshl_add_u64 v[68:69], v[68:69], 0, s[68:69]
	v_lshlrev_b64 v[66:67], 1, v[66:67]
	v_or_b32_e32 v74, v121, v122
	v_subrev_u32_e32 v75, s22, v160
	v_lshl_add_u64 v[70:71], v[162:163], 0, v[66:67]
	v_mul_u32_u24_e32 v76, 0x1a00, v74
	v_lshlrev_b32_e32 v77, 14, v74
	v_add_u32_e32 v76, v76, v75
	v_add_u32_e32 v77, v77, v75
	v_sub_co_u32_e32 v68, vcc, v68, v76
	s_nop 1
	v_subbrev_co_u32_e32 v69, vcc, 0, v69, vcc
	v_sub_co_u32_e32 v70, vcc, v70, v77
	s_nop 1
	v_subbrev_co_u32_e32 v71, vcc, 0, v71, vcc
	v_mov_b32_e32 v160, v76
	v_readfirstlane_b32 s98, v68
	v_readfirstlane_b32 s99, v69
	v_readfirstlane_b32 s100, v70
	v_readfirstlane_b32 s101, v71
	v_readfirstlane_b32 s87, v177
	v_add_u32_e32 v161, 0x1a000, v76
	v_add_u32_e32 v162, 0x34000, v76
	v_add_u32_e32 v163, 0x4e000, v76
	v_mov_b32_e32 v164, v77
	v_add_u32_e32 v165, 0x40000, v77
	v_add_u32_e32 v166, 0x80000, v77
	v_add_u32_e32 v167, 0xc0000, v77
	s_movk_i32 s64, 0x2000
	s_mov_b32 s65, 0
	s_mov_b64 s[40:41], 0
	s_mov_b64 s[42:43], s[4:5]
	s_branch .LBB0_279
	s_nop 0
	s_nop 0
	s_nop 0
	s_nop 0
